# dn_pre 16x16 diagonal-block inversion: all 36 LDS row reads issued up front, substitution behind counted waits (was ~40 exposed LDS round trips)
# speedup vs baseline: 1.0343x; 1.0073x over previous
.LBB0_417:
	s_waitcnt lgkmcnt(0)
	s_barrier
	s_and_saveexec_b64 s[36:37], vcc
	s_cbranch_execz .LBB0_419
	v_and_b32_e32 v5, -16, v0
	s_movk_i32 s1, 0x110
	v_mul_lo_u32 v6, v5, s1
	v_lshl_add_u32 v32, v5, 2, v6
	ds_read_b128 v[36:39], v32 offset:33792
	ds_read_b128 v[40:43], v32 offset:33808
	ds_read_b128 v[80:83], v32 offset:33824
	ds_read_b128 v[84:87], v32 offset:33840
	ds_read_b128 v[88:91], v32 offset:34064
	ds_read_b128 v[92:95], v32 offset:34080
	ds_read_b128 v[96:99], v32 offset:34096
	ds_read_b128 v[100:103], v32 offset:34112
	ds_read_b128 v[104:107], v32 offset:34336
	ds_read_b128 v[108:111], v32 offset:34352
	ds_read_b128 v[112:115], v32 offset:34368
	ds_read_b128 v[116:119], v32 offset:34384
	ds_read_b128 v[120:123], v32 offset:34624
	ds_read_b128 v[124:127], v32 offset:34640
	ds_read_b128 v[128:131], v32 offset:34656
	ds_read_b128 v[132:135], v32 offset:34896
	ds_read_b128 v[136:139], v32 offset:34912
	ds_read_b128 v[140:143], v32 offset:34928
	ds_read_b128 v[144:147], v32 offset:35168
	ds_read_b128 v[148:151], v32 offset:35184
	ds_read_b128 v[152:155], v32 offset:35200
	ds_read_b128 v[156:159], v32 offset:35440
	ds_read_b128 v[160:163], v32 offset:35456
	ds_read_b128 v[164:167], v32 offset:35472
	ds_read_b128 v[202:205], v32 offset:35728
	ds_read_b128 v[206:209], v32 offset:35744
	ds_read_b128 v[210:213], v32 offset:36000
	ds_read_b128 v[214:217], v32 offset:36016
	ds_read_b128 v[218:221], v32 offset:36272
	ds_read_b128 v[222:225], v32 offset:36288
	ds_read_b128 v[226:229], v32 offset:36544
	ds_read_b128 v[230:233], v32 offset:36560
	ds_read_b128 v[234:237], v32 offset:36832
	ds_read_b128 v[238:241], v32 offset:37104
	ds_read_b128 v[242:245], v32 offset:37376
	ds_read_b128 v[246:249], v32 offset:37648
	v_cmp_eq_u32_e32 vcc, 0, v3
	s_nop 1
	v_cndmask_b32_e64 v4, 0, 1.0, vcc
	v_cmp_eq_u32_e32 vcc, 1, v3
	s_nop 1
	v_cndmask_b32_e64 v5, 0, 1.0, vcc
	v_cmp_eq_u32_e32 vcc, 2, v3
	s_nop 1
	v_cndmask_b32_e64 v6, 0, 1.0, vcc
	v_cmp_eq_u32_e32 vcc, 3, v3
	s_nop 1
	v_cndmask_b32_e64 v7, 0, 1.0, vcc
	v_cmp_eq_u32_e32 vcc, 4, v3
	s_nop 1
	v_cndmask_b32_e64 v8, 0, 1.0, vcc
	v_cmp_eq_u32_e32 vcc, 5, v3
	s_nop 1
	v_cndmask_b32_e64 v9, 0, 1.0, vcc
	v_cmp_eq_u32_e32 vcc, 6, v3
	s_nop 1
	v_cndmask_b32_e64 v10, 0, 1.0, vcc
	v_cmp_eq_u32_e32 vcc, 7, v3
	s_nop 1
	v_cndmask_b32_e64 v11, 0, 1.0, vcc
	v_cmp_eq_u32_e32 vcc, 8, v3
	s_nop 1
	v_cndmask_b32_e64 v12, 0, 1.0, vcc
	v_cmp_eq_u32_e32 vcc, 9, v3
	s_nop 1
	v_cndmask_b32_e64 v13, 0, 1.0, vcc
	v_cmp_eq_u32_e32 vcc, 10, v3
	s_nop 1
	v_cndmask_b32_e64 v14, 0, 1.0, vcc
	v_cmp_eq_u32_e32 vcc, 11, v3
	s_nop 1
	v_cndmask_b32_e64 v15, 0, 1.0, vcc
	v_cmp_eq_u32_e32 vcc, 12, v3
	s_nop 1
	v_cndmask_b32_e64 v16, 0, 1.0, vcc
	v_cmp_eq_u32_e32 vcc, 13, v3
	s_nop 1
	v_cndmask_b32_e64 v17, 0, 1.0, vcc
	v_cmp_eq_u32_e32 vcc, 14, v3
	s_nop 1
	v_cndmask_b32_e64 v18, 0, 1.0, vcc
	v_cmp_eq_u32_e32 vcc, 15, v3
	s_nop 1
	v_cndmask_b32_e64 v19, 0, 1.0, vcc
	s_waitcnt lgkmcnt(15)
	v_fma_f32 v5, -v4, v37, v5
	v_fma_f32 v6, -v4, v38, v6
	v_fma_f32 v7, -v4, v39, v7
	v_fma_f32 v8, -v4, v40, v8
	v_fma_f32 v9, -v4, v41, v9
	v_fma_f32 v10, -v4, v42, v10
	v_fma_f32 v11, -v4, v43, v11
	v_fma_f32 v12, -v4, v80, v12
	v_fma_f32 v13, -v4, v81, v13
	v_fma_f32 v14, -v4, v82, v14
	v_fma_f32 v15, -v4, v83, v15
	v_fma_f32 v16, -v4, v84, v16
	v_fma_f32 v17, -v4, v85, v17
	v_fma_f32 v18, -v4, v86, v18
	v_fma_f32 v19, -v4, v87, v19
	s_waitcnt lgkmcnt(15)
	v_fma_f32 v6, -v5, v90, v6
	v_fma_f32 v7, -v5, v91, v7
	v_fma_f32 v8, -v5, v92, v8
	v_fma_f32 v9, -v5, v93, v9
	v_fma_f32 v10, -v5, v94, v10
	v_fma_f32 v11, -v5, v95, v11
	v_fma_f32 v12, -v5, v96, v12
	v_fma_f32 v13, -v5, v97, v13
	v_fma_f32 v14, -v5, v98, v14
	v_fma_f32 v15, -v5, v99, v15
	v_fma_f32 v16, -v5, v100, v16
	v_fma_f32 v17, -v5, v101, v17
	v_fma_f32 v18, -v5, v102, v18
	v_fma_f32 v19, -v5, v103, v19
	s_waitcnt lgkmcnt(15)
	v_fma_f32 v7, -v6, v107, v7
	v_fma_f32 v8, -v6, v108, v8
	v_fma_f32 v9, -v6, v109, v9
	v_fma_f32 v10, -v6, v110, v10
	v_fma_f32 v11, -v6, v111, v11
	v_fma_f32 v12, -v6, v112, v12
	v_fma_f32 v13, -v6, v113, v13
	v_fma_f32 v14, -v6, v114, v14
	v_fma_f32 v15, -v6, v115, v15
	v_fma_f32 v16, -v6, v116, v16
	v_fma_f32 v17, -v6, v117, v17
	v_fma_f32 v18, -v6, v118, v18
	v_fma_f32 v19, -v6, v119, v19
	s_waitcnt lgkmcnt(15)
	v_fma_f32 v8, -v7, v120, v8
	v_fma_f32 v9, -v7, v121, v9
	v_fma_f32 v10, -v7, v122, v10
	v_fma_f32 v11, -v7, v123, v11
	v_fma_f32 v12, -v7, v124, v12
	v_fma_f32 v13, -v7, v125, v13
	v_fma_f32 v14, -v7, v126, v14
	v_fma_f32 v15, -v7, v127, v15
	v_fma_f32 v16, -v7, v128, v16
	v_fma_f32 v17, -v7, v129, v17
	v_fma_f32 v18, -v7, v130, v18
	v_fma_f32 v19, -v7, v131, v19
	s_waitcnt lgkmcnt(15)
	v_fma_f32 v9, -v8, v133, v9
	v_fma_f32 v10, -v8, v134, v10
	v_fma_f32 v11, -v8, v135, v11
	v_fma_f32 v12, -v8, v136, v12
	v_fma_f32 v13, -v8, v137, v13
	v_fma_f32 v14, -v8, v138, v14
	v_fma_f32 v15, -v8, v139, v15
	v_fma_f32 v16, -v8, v140, v16
	v_fma_f32 v17, -v8, v141, v17
	v_fma_f32 v18, -v8, v142, v18
	v_fma_f32 v19, -v8, v143, v19
	s_waitcnt lgkmcnt(15)
	v_fma_f32 v10, -v9, v146, v10
	v_fma_f32 v11, -v9, v147, v11
	v_fma_f32 v12, -v9, v148, v12
	v_fma_f32 v13, -v9, v149, v13
	v_fma_f32 v14, -v9, v150, v14
	v_fma_f32 v15, -v9, v151, v15
	v_fma_f32 v16, -v9, v152, v16
	v_fma_f32 v17, -v9, v153, v17
	v_fma_f32 v18, -v9, v154, v18
	v_fma_f32 v19, -v9, v155, v19
	s_waitcnt lgkmcnt(12)
	v_fma_f32 v11, -v10, v159, v11
	v_fma_f32 v12, -v10, v160, v12
	v_fma_f32 v13, -v10, v161, v13
	v_fma_f32 v14, -v10, v162, v14
	v_fma_f32 v15, -v10, v163, v15
	v_fma_f32 v16, -v10, v164, v16
	v_fma_f32 v17, -v10, v165, v17
	v_fma_f32 v18, -v10, v166, v18
	v_fma_f32 v19, -v10, v167, v19
	s_waitcnt lgkmcnt(10)
	v_fma_f32 v12, -v11, v202, v12
	v_fma_f32 v13, -v11, v203, v13
	v_fma_f32 v14, -v11, v204, v14
	v_fma_f32 v15, -v11, v205, v15
	v_fma_f32 v16, -v11, v206, v16
	v_fma_f32 v17, -v11, v207, v17
	v_fma_f32 v18, -v11, v208, v18
	v_fma_f32 v19, -v11, v209, v19
	s_waitcnt lgkmcnt(8)
	v_fma_f32 v13, -v12, v211, v13
	v_fma_f32 v14, -v12, v212, v14
	v_fma_f32 v15, -v12, v213, v15
	v_fma_f32 v16, -v12, v214, v16
	v_fma_f32 v17, -v12, v215, v17
	v_fma_f32 v18, -v12, v216, v18
	v_fma_f32 v19, -v12, v217, v19
	s_waitcnt lgkmcnt(6)
	v_fma_f32 v14, -v13, v220, v14
	v_fma_f32 v15, -v13, v221, v15
	v_fma_f32 v16, -v13, v222, v16
	v_fma_f32 v17, -v13, v223, v17
	v_fma_f32 v18, -v13, v224, v18
	v_fma_f32 v19, -v13, v225, v19
	s_waitcnt lgkmcnt(4)
	v_fma_f32 v15, -v14, v229, v15
	v_fma_f32 v16, -v14, v230, v16
	v_fma_f32 v17, -v14, v231, v17
	v_fma_f32 v18, -v14, v232, v18
	v_fma_f32 v19, -v14, v233, v19
	s_waitcnt lgkmcnt(3)
	v_fma_f32 v16, -v15, v234, v16
	v_fma_f32 v17, -v15, v235, v17
	v_fma_f32 v18, -v15, v236, v18
	v_fma_f32 v19, -v15, v237, v19
	s_waitcnt lgkmcnt(2)
	v_fma_f32 v17, -v16, v239, v17
	v_fma_f32 v18, -v16, v240, v18
	v_fma_f32 v19, -v16, v241, v19
	s_waitcnt lgkmcnt(1)
	v_fma_f32 v18, -v17, v244, v18
	v_fma_f32 v19, -v17, v245, v19
	s_waitcnt lgkmcnt(0)
	v_fma_f32 v19, -v18, v249, v19
	v_lshlrev_b32_e32 v20, 2, v30
	ds_write_b128 v20, v[4:7] offset:51200
	ds_write_b128 v20, v[8:11] offset:51216
	ds_write_b128 v20, v[12:15] offset:51232
	ds_write_b128 v20, v[16:19] offset:51248
